# opt31: opt26 + first (peeled) diff-attention iteration: tiles 2,3 LDS-DMA pieces moved from the post-barrier head to between tile 0 and tile 1
# baseline (speedup 1.0000x reference)
; #define DMA_T(s_) do { DMA_K(s_); DMA_V(s_); } while (0)
; #define CLASSIFY(kv0_, act_, cls_) do { act_ = true; if (SWA) act_ = ((kv0_) + 63 >= qw - 128) && ((kv0_) <= qw + 159); \
;         cls_ = 0; if ((kv0_) + 63 < qw) cls_ = 1; else if ((kv0_) > qw + 31) cls_ = 2; \
;         if (SWA) { if (cls_ == 1 && qw + 31 - (kv0_) > 128) cls_ = 0; if (cls_ == 2 && (kv0_) + 63 - qw > 128) cls_ = 0; } } while (0)
; template <bool SWA>
; __device__ __forceinline__ void unit(LAS unsigned char* lds, const bf16_t* PROJ, const bf16_t* KT, const bf16_t* VT, bf16_t* OB, int opitch, int ocol, int b, int head, int qb, float slope2, float m_init, float lam, const float* subg) {
;     ...
;     for (int S = 0; S < npairs; ++S) {
;         const int sa = 2 * S, sb = 2 * S + 1;
;         if (sa + 2 < nsteps) DMA_T(sa + 2);
;         if (sb + 2 < nsteps) DMA_T(sb + 2);
;         const int kva = TILE_OF(sa) * 64, kvb = TILE_OF(sb < nsteps ? sb : sa) * 64;
;         bool acta, actb; int clsa, clsb;
;         CLASSIFY(kva, acta, clsa); CLASSIFY(kvb, actb, clsb); actb = actb && (sb < nsteps);
;         f32x16 s0, s1, u0, u1;
;         if (acta) QK_T(s0, s1, sa, clsa);
.Ldq_nopf:
	s_or_b32 s0, s42, 63
	s_cmp_ge_u32 s0, s5
	s_cselect_b64 s[6:7], -1, 0
	s_cmp_lt_u32 s0, s5
	s_cselect_b64 s[82:83], -1, 0
	s_cmp_le_u32 s42, s19
	s_cselect_b64 s[78:79], -1, 0
	s_and_b64 s[84:85], s[6:7], s[78:79]
	s_and_b64 vcc, exec, s[84:85]
	v_mov_b32_e32 v64, 0
	s_cbranch_vccnz .LBB0_851
	s_and_b64 s[0:1], s[78:79], exec
	s_cselect_b32 s3, 0, 64
	s_and_b64 s[0:1], s[6:7], exec
	s_cselect_b32 s0, s3, 0
	s_add_i32 s0, s0, 0
	s_add_i32 s0, s0, 0x20200
	v_mov_b32_e32 v12, s0
	ds_read_b128 v[0:3], v12
	ds_read_b128 v[4:7], v12 offset:16
	ds_read_b128 v[8:11], v12 offset:32
	ds_read_b128 v[12:15], v12 offset:48
	s_branch .LBB0_852

; template <bool SWA>
; __device__ __forceinline__ void unit(LAS unsigned char* lds, const bf16_t* PROJ, const bf16_t* KT, const bf16_t* VT, bf16_t* OB, int opitch, int ocol, int b, int head, int qb, float slope2, float m_init, float lam, const float* subg) {
;     ...
;         if (acta) { SM_T(s0, s1, kva, clsa); if (pvalid) PV_TILE(sa); }
;         if (actb) { SM_T(u0, u1, kvb, clsb); if (pvalid) PV_TILE(sb); }
.LBB0_868:
	s_cmp_eq_u32 s16, 0
	s_cselect_b32 s30, 0x8000, 0
	s_mov_b32 s31, 0x4000
	s_cselect_b32 s31, 0xc000, s31
	s_add_u32 s98, s73, s30
	s_addc_u32 s99, s17, 0
	s_add_i32 m0, s33, 0x8000
	s_nop 0
	global_load_lds_dwordx4 v164, s[98:99]
	s_add_i32 m0, s33, 0x8400
	s_nop 0
	global_load_lds_dwordx4 v170, s[98:99]
	s_add_u32 s98, s2, s30
	s_addc_u32 s99, s23, 0
	s_add_i32 m0, s33, 0x18000
	s_nop 0
	global_load_lds_dwordx4 v168, s[98:99]
	s_add_i32 m0, s33, 0x18400
	s_nop 0
	global_load_lds_dwordx4 v172, s[98:99]
	s_add_u32 s98, s73, s31
	s_addc_u32 s99, s17, 0
	s_add_i32 m0, s33, 0xc000
	s_nop 0
	global_load_lds_dwordx4 v164, s[98:99]
	s_add_i32 m0, s33, 0xc400
	s_nop 0
	global_load_lds_dwordx4 v170, s[98:99]
	s_add_u32 s98, s2, s31
	s_addc_u32 s99, s23, 0
	s_add_i32 m0, s33, 0x1c000
	s_nop 0
	global_load_lds_dwordx4 v168, s[98:99]
	s_add_i32 m0, s33, 0x1c400
	s_nop 0
	global_load_lds_dwordx4 v172, s[98:99]
	v_or_b32_e32 v96, s0, v187
	v_sub_u32_e32 v96, v188, v96
	v_cvt_f32_i32_e32 v99, v96
	s_xor_b64 s[0:1], s[80:81], -1
	s_andn2_b64 vcc, exec, s[0:1]
	s_mov_b64 s[6:7], -1
	s_cbranch_vccnz .LBB0_874
	s_andn2_b64 vcc, exec, s[78:79]
	s_cbranch_vccnz .LBB0_871
	v_mul_f32_e64 v97, -s76, v99
	v_fma_f32 v98, -s76, v99, v194
	s_mov_b64 s[6:7], 0
